# P0 w_in transpose: 8 weight-row + 8 g_norm loads issued together, one wait (was 8 serial round trips)
# speedup vs baseline: 1.0340x; 1.0042x over previous
.LBB0_24:
	s_lshl_b32 s6, s6, 6
	v_cmp_lt_i32_e64 s[0:1], -1, v34
	v_or_b32_e32 v38, s6, v44
	v_lshl_add_u64 v[40:41], v[34:35], 2, s[16:17]
	v_ashrrev_i32_e32 v39, 31, v38
	v_lshl_add_u64 v[100:101], v[38:39], 2, s[50:51]
	v_mov_b32_e32 v0, 0
	v_mov_b32_e32 v1, 0
	v_mov_b32_e32 v2, 0
	v_mov_b32_e32 v3, 0
	v_mov_b32_e32 v4, 0
	v_mov_b32_e32 v5, 0
	v_mov_b32_e32 v6, 0
	v_mov_b32_e32 v7, 0
	v_mov_b32_e32 v8, 0
	v_mov_b32_e32 v9, 0
	v_mov_b32_e32 v10, 0
	v_mov_b32_e32 v11, 0
	v_mov_b32_e32 v12, 0
	v_mov_b32_e32 v13, 0
	v_mov_b32_e32 v14, 0
	v_mov_b32_e32 v15, 0
	v_mov_b32_e32 v16, 0
	v_mov_b32_e32 v17, 0
	v_mov_b32_e32 v18, 0
	v_mov_b32_e32 v19, 0
	v_mov_b32_e32 v20, 0
	v_mov_b32_e32 v21, 0
	v_mov_b32_e32 v22, 0
	v_mov_b32_e32 v23, 0
	v_mov_b32_e32 v24, 0
	v_mov_b32_e32 v25, 0
	v_mov_b32_e32 v26, 0
	v_mov_b32_e32 v27, 0
	v_mov_b32_e32 v28, 0
	v_mov_b32_e32 v29, 0
	v_mov_b32_e32 v30, 0
	v_mov_b32_e32 v31, 0
	s_and_saveexec_b64 s[8:9], s[0:1]
	v_mad_i64_i32 v[102:103], s[34:35], v38, s14, v[40:41]
	global_load_dwordx4 v[4:7], v[102:103], off
	v_or_b32_e32 v104, 8, v38
	v_mad_i64_i32 v[104:105], s[34:35], v104, s14, v[40:41]
	global_load_dwordx4 v[0:3], v[104:105], off
	v_or_b32_e32 v106, 16, v38
	v_mad_i64_i32 v[106:107], s[34:35], v106, s14, v[40:41]
	global_load_dwordx4 v[12:15], v[106:107], off
	v_or_b32_e32 v108, 24, v38
	v_mad_i64_i32 v[108:109], s[34:35], v108, s14, v[40:41]
	global_load_dwordx4 v[8:11], v[108:109], off
	v_or_b32_e32 v110, 32, v38
	v_mad_i64_i32 v[110:111], s[34:35], v110, s14, v[40:41]
	global_load_dwordx4 v[20:23], v[110:111], off
	v_or_b32_e32 v112, 40, v38
	v_mad_i64_i32 v[112:113], s[34:35], v112, s14, v[40:41]
	global_load_dwordx4 v[16:19], v[112:113], off
	v_or_b32_e32 v114, 48, v38
	v_mad_i64_i32 v[114:115], s[34:35], v114, s14, v[40:41]
	global_load_dwordx4 v[28:31], v[114:115], off
	v_or_b32_e32 v116, 56, v38
	v_mad_i64_i32 v[116:117], s[34:35], v116, s14, v[40:41]
	global_load_dwordx4 v[24:27], v[116:117], off
	s_andn2_b64 vcc, exec, s[4:5]
	s_cbranch_vccnz .Lp0w_noscale
	global_load_dword v120, v[100:101], off
	global_load_dword v122, v[100:101], off offset:32
	global_load_dword v124, v[100:101], off offset:64
	global_load_dword v126, v[100:101], off offset:96
	global_load_dword v128, v[100:101], off offset:128
	global_load_dword v130, v[100:101], off offset:160
	global_load_dword v132, v[100:101], off offset:192
	global_load_dword v134, v[100:101], off offset:224
	s_waitcnt vmcnt(0)
	v_pk_mul_f32 v[6:7], v[6:7], v[120:121] op_sel_hi:[1,0]
	v_pk_mul_f32 v[4:5], v[4:5], v[120:121] op_sel_hi:[1,0]
	v_pk_mul_f32 v[2:3], v[2:3], v[122:123] op_sel_hi:[1,0]
	v_pk_mul_f32 v[0:1], v[0:1], v[122:123] op_sel_hi:[1,0]
	v_pk_mul_f32 v[14:15], v[14:15], v[124:125] op_sel_hi:[1,0]
	v_pk_mul_f32 v[12:13], v[12:13], v[124:125] op_sel_hi:[1,0]
	v_pk_mul_f32 v[10:11], v[10:11], v[126:127] op_sel_hi:[1,0]
	v_pk_mul_f32 v[8:9], v[8:9], v[126:127] op_sel_hi:[1,0]
	v_pk_mul_f32 v[22:23], v[22:23], v[128:129] op_sel_hi:[1,0]
	v_pk_mul_f32 v[20:21], v[20:21], v[128:129] op_sel_hi:[1,0]
	v_pk_mul_f32 v[18:19], v[18:19], v[130:131] op_sel_hi:[1,0]
	v_pk_mul_f32 v[16:17], v[16:17], v[130:131] op_sel_hi:[1,0]
	v_pk_mul_f32 v[30:31], v[30:31], v[132:133] op_sel_hi:[1,0]
	v_pk_mul_f32 v[28:29], v[28:29], v[132:133] op_sel_hi:[1,0]
	v_pk_mul_f32 v[26:27], v[26:27], v[134:135] op_sel_hi:[1,0]
	v_pk_mul_f32 v[24:25], v[24:25], v[134:135] op_sel_hi:[1,0]
.Lp0w_noscale:
	s_branch .LBB0_11

.LBB0_537:
	s_or_b64 exec, exec, s[0:1]
	s_and_b64 s[0:1], s[36:37], exec
	s_cselect_b32 s28, 16, 0x1000
	s_add_u32 s64, s76, 0x13d00000
	s_addc_u32 s65, s77, 0
	s_bfe_u32 s68, s96, 0x20006
	s_mul_i32 s0, s68, 0x3700
	s_add_i32 s71, s0, 0
	s_and_b32 s0, s96, 0xffffff00
	s_lshr_b32 s74, s96, 8
	s_add_i32 s84, s0, 0
	s_lshl_b32 s11, s74, 5
	s_add_i32 s80, s84, 0x12600
	s_cmpk_lt_u32 s96, 0x540
	v_readlane_b32 s20, v255, 31
	s_cselect_b64 s[40:41], -1, 0
	s_add_i32 s12, s20, -4
	s_lshl_b32 s13, s12, 2
	s_lshl_b32 s22, s12, 10
	s_cmpk_lt_u32 s96, 0x440
	s_cselect_b64 s[42:43], -1, 0
	s_lshl_b32 s66, s20, 10
	s_cmpk_lt_u32 s96, 0x340
	s_cselect_b64 s[46:47], -1, 0
	s_add_i32 s14, s20, 4
	s_lshl_b32 s15, s14, 2
	s_lshl_b32 s23, s14, 10
	s_cmpk_lt_u32 s96, 0x240
	s_cselect_b64 s[48:49], -1, 0
	s_add_i32 s16, s20, 8
	s_lshl_b32 s17, s16, 2
	s_lshl_b32 s24, s16, 10
	s_cmp_eq_u32 s20, 4
	s_cselect_b64 s[50:51], -1, 0
	s_cmp_eq_u32 s20, 2
	s_mov_b32 s0, 0xfc00000
	s_cselect_b32 s38, s0, 0x13d00000
	s_add_u32 s8, s76, s6
	s_addc_u32 s9, s77, 0
	s_mul_i32 s0, s20, 0x2400
	s_add_i32 s1, 0, 0x1a900
	s_add_i32 s81, s1, s0
	s_lshl_b32 s0, s74, 7
	s_add_i32 s83, s0, 0
	s_add_i32 s82, s81, 0x2000
	s_add_i32 s83, s83, 0x14800
	s_add_i32 s84, s84, 0x12400
	s_lshl_b32 s29, s20, 5
	s_add_u32 s6, s64, s6
	s_addc_u32 s7, s65, 0
	s_lshl_b32 s85, s33, 10
	s_add_u32 s18, s76, 0x10000
	v_writelane_b32 v255, s96, 33
	s_addc_u32 s19, s77, 0
	v_lshl_or_b32 v11, s68, 4, v9
	v_writelane_b32 v255, s18, 34
	v_add_u32_e32 v25, 1, v11
	v_lshlrev_b32_e32 v27, 3, v38
	v_writelane_b32 v255, s19, 35
	v_lshlrev_b32_e32 v10, 7, v25
	v_and_b32_e32 v22, 8, v27
	s_add_i32 s0, 0, 0x1cd00
	s_add_i32 s18, 0, 0x1f100
	v_add3_u32 v91, s1, v10, v22
	v_add3_u32 v92, s0, v10, v22
	v_add3_u32 v93, s18, v10, v22
	v_lshlrev_b32_e32 v10, 8, v25
	s_add_i32 s19, 0, 0x23900
	v_add3_u32 v28, s19, v10, v22
	v_lshlrev_b32_e32 v10, 7, v11
	v_add3_u32 v94, s1, v10, v22
	v_add3_u32 v95, s0, v10, v22
	v_add3_u32 v96, s18, v10, v22
	v_lshlrev_b32_e32 v10, 8, v11
	v_add3_u32 v29, s19, v10, v22
	v_add_u32_e32 v10, 1, v89
	s_add_i32 s19, 0, 0x21500
	v_lshl_add_u32 v32, v10, 7, s19
	v_xor_b32_e32 v10, v10, v39
	v_lshlrev_b32_e32 v10, 4, v10
	v_and_b32_e32 v33, 0x70, v10
	v_lshlrev_b32_e32 v10, 7, v89
	v_add_u32_e32 v34, s19, v10
	s_add_i32 s19, 0, 0x12800
	s_cmp_lg_u32 s12, 16
	v_add_u32_e32 v36, s19, v10
	v_or_b32_e32 v10, s13, v38
	s_cselect_b64 vcc, -1, 0
	v_xor_b32_e32 v22, v89, v39
	v_cndmask_b32_e32 v98, 64, v10, vcc
	v_bitop3_b32 v10, v38, v39, s13 bitop3:0x36
	v_lshlrev_b32_e32 v22, 4, v22
	v_and_or_b32 v10, v10, 7, v41
	v_and_b32_e32 v35, 0x70, v22
	v_lshlrev_b32_e32 v22, 4, v10
	v_mov_b32_e32 v10, 0
	v_mov_b32_e32 v23, v10
	s_cmp_lg_u32 s20, 16
	v_lshl_add_u64 v[48:49], s[4:5], 0, v[22:23]
	v_or_b32_e32 v22, s3, v38
	s_cselect_b64 vcc, -1, 0
	v_cndmask_b32_e32 v99, 64, v22, vcc
	v_bitop3_b32 v22, v38, v39, s3 bitop3:0x36
	v_and_or_b32 v22, v22, 7, v41
	v_lshlrev_b32_e32 v22, 4, v22
	s_cmp_lg_u32 s14, 16
	v_lshl_add_u64 v[50:51], s[4:5], 0, v[22:23]
	v_or_b32_e32 v22, s15, v38
	s_cselect_b64 vcc, -1, 0
	v_cndmask_b32_e32 v100, 64, v22, vcc
	v_bitop3_b32 v22, v38, v39, s15 bitop3:0x36
	v_and_or_b32 v22, v22, 7, v41
	v_lshlrev_b32_e32 v22, 4, v22
	s_cmp_lg_u32 s16, 16
	v_lshl_add_u64 v[52:53], s[4:5], 0, v[22:23]
	v_or_b32_e32 v22, s17, v38
	s_cselect_b64 vcc, -1, 0
	v_cndmask_b32_e32 v101, 64, v22, vcc
	v_bitop3_b32 v22, v38, v39, s17 bitop3:0x36
	v_and_or_b32 v22, v22, 7, v41
	v_lshlrev_b32_e32 v22, 4, v22
	v_lshl_add_u64 v[54:55], s[4:5], 0, v[22:23]
	v_xor_b32_e32 v22, v38, v20
	s_movk_i32 s10, 0x3700
	v_or_b32_e32 v22, v22, v41
	v_lshlrev_b32_e32 v41, 5, v9
	v_lshrrev_b32_e32 v45, 7, v42
	v_cmp_gt_u32_e64 s[0:1], 16, v40
	v_or_b32_e32 v103, v27, v41
	v_lshl_add_u32 v104, v40, 2, s71
	v_add_u32_e32 v40, s71, v41
	v_lshrrev_b32_e32 v41, 2, v9
	v_mul_lo_u32 v45, v45, s10
	v_or_b32_e32 v41, v90, v41
	v_add_u32_e32 v67, 0, v45
	v_bfe_u32 v45, v42, 3, 4
	v_mul_u32_u24_e32 v41, 0x48, v41
	v_and_b32_e32 v21, 12, v21
	v_mul_u32_u24_e32 v45, 0x48, v45
	v_or_b32_e32 v24, s11, v90
	v_add_lshl_u32 v105, v21, v41, 1
	v_lshl_or_b32 v21, v89, 6, v8
	v_add_lshl_u32 v8, v45, v8, 1
	v_mov_b32_e32 v45, v10
	v_and_b32_e32 v26, 7, v25
	v_lshl_add_u64 v[60:61], s[6:7], 0, v[44:45]
	v_cmp_eq_u32_e64 s[6:7], 0, v42
	v_lshrrev_b32_e32 v42, 3, v24
	v_and_b32_e32 v62, 8, v42
	v_bitop3_b32 v63, v42, v26, 5 bitop3:0x6c
	v_or_b32_e32 v63, v63, v62
	v_lshlrev_b32_e32 v68, 4, v63
	v_add_u32_e32 v63, 64, v24
	v_bitop3_b32 v45, v42, v25, 7 bitop3:0x78
	v_lshrrev_b32_e32 v64, 3, v63
	v_xor_b32_e32 v69, v42, v20
	v_bitop3_b32 v42, v42, v20, 5 bitop3:0x6c
	v_and_b32_e32 v65, 8, v64
	v_or_b32_e32 v42, v42, v62
	v_bitop3_b32 v62, v64, v20, 5 bitop3:0x6c
	v_or_b32_e32 v62, v62, v65
	v_lshlrev_b32_e32 v108, 4, v69
	v_lshlrev_b32_e32 v69, 4, v62
	v_or_b32_e32 v62, 16, v24
	v_lshlrev_b32_e32 v22, 4, v22
	v_lshlrev_b32_e32 v71, 1, v63
	v_lshrrev_b32_e32 v63, 3, v62
	v_lshl_add_u64 v[56:57], s[4:5], 0, v[22:23]
	v_xor_b32_e32 v22, v88, v20
	v_bitop3_b32 v26, v64, v26, 5 bitop3:0x6c
	v_bitop3_b32 v64, v63, v25, 7 bitop3:0x78
	v_lshlrev_b32_e32 v22, 4, v22
	v_or_b32_e32 v26, v26, v65
	v_lshlrev_b32_e32 v111, 4, v64
	v_and_b32_e32 v64, 8, v63
	v_bitop3_b32 v65, v63, v25, 7 bitop3:0x28
	s_movk_i32 s18, 0x48
	v_lshl_add_u64 v[58:59], s[8:9], 0, v[22:23]
	v_or_b32_e32 v23, s11, v9
	v_or_b32_e32 v65, v65, v64
	v_mul_u32_u24_e32 v30, 0x48, v11
	v_mul_u32_u24_e32 v31, 0x48, v9
	v_lshlrev_b32_e32 v97, 2, v11
	v_or_b32_e32 v22, 16, v90
	v_lshlrev_b32_e32 v72, 4, v65
	v_add_u32_e32 v65, 0x50, v24
	v_mul_lo_u32 v23, v23, s18
	v_mad_u32_u24 v11, v11, s18, 32
	v_lshlrev_b32_e32 v70, 1, v24
	v_add_lshl_u32 v109, v24, v30, 1
	v_add_lshl_u32 v110, v24, v31, 1
	v_lshrrev_b32_e32 v73, 3, v65
	v_xor_b32_e32 v75, v63, v20
	v_bitop3_b32 v63, v63, v20, 7 bitop3:0x6c
	v_add_lshl_u32 v113, v62, v30, 1
	v_add_lshl_u32 v115, v30, v90, 1
	v_add_lshl_u32 v116, v22, v30, 1
	v_add_u32_e32 v30, 0x480, v23
	v_add_lshl_u32 v119, v11, v90, 1
	v_add_lshl_u32 v120, v11, v22, 1
	v_or_b32_e32 v11, 32, v90
	v_lshlrev_b32_e32 v123, 2, v24
	v_or_b32_e32 v24, 1, v90
	v_cmp_eq_u32_e32 vcc, v90, v9
	v_lshlrev_b32_e32 v106, 5, v20
	v_and_b32_e32 v74, 8, v73
	v_bitop3_b32 v25, v73, v25, 7 bitop3:0x28
	v_or_b32_e32 v63, v63, v64
	v_bitop3_b32 v20, v73, v20, 7 bitop3:0x6c
	v_lshlrev_b32_e32 v73, 1, v62
	v_add_lshl_u32 v114, v62, v31, 1
	v_add_lshl_u32 v118, v30, v90, 1
	v_add_lshl_u32 v122, v11, v30, 1
	v_lshlrev_b32_e32 v124, 2, v62
	v_or_b32_e32 v30, 2, v90
	v_cndmask_b32_e64 v62, 0, 1.0, vcc
	v_cmp_eq_u32_e32 vcc, v24, v9
	v_lshlrev_b32_e32 v112, 4, v75
	v_lshlrev_b32_e32 v75, 4, v63
	v_add_lshl_u32 v117, v90, v23, 1
	v_add_lshl_u32 v121, v11, v23, 1
	v_add_lshl_u32 v125, v90, v31, 1
	v_add_lshl_u32 v23, v11, v31, 1
	v_or_b32_e32 v31, 3, v90
	v_cndmask_b32_e64 v63, 0, 1.0, vcc
	v_cmp_eq_u32_e32 vcc, v30, v9
	v_cmp_eq_u32_e64 s[4:5], 0, v9
	v_mad_u32_u24 v37, v9, s18, 16
	v_cmp_lt_u32_e64 s[8:9], v90, v9
	v_cmp_gt_u32_e64 s[10:11], v90, v9
	v_cmp_lt_u32_e64 s[12:13], v24, v9
	v_cmp_lt_u32_e64 s[14:15], v30, v9
	v_cmp_gt_u32_e64 s[16:17], v30, v9
	v_cmp_lt_u32_e64 s[18:19], v31, v9
	v_cmp_gt_u32_e64 s[20:21], v31, v9
	v_cndmask_b32_e64 v64, 0, 1.0, vcc
	v_cmp_eq_u32_e32 vcc, v31, v9
	v_lshlrev_b32_e32 v9, 2, v9
	v_lshl_add_u32 v24, v38, 10, s97
	s_mov_b32 s3, 0xdc00
	v_add3_u32 v126, v24, v9, s3
	v_and_b32_e32 v9, 3, v39
	s_movk_i32 s25, 0x2400
	v_lshlrev_b32_e32 v43, 2, v21
	v_lshlrev_b32_e32 v21, 1, v21
	v_lshl_or_b32 v9, v9, 3, s29
	v_lshlrev_b32_e32 v24, 1, v41
	s_waitcnt lgkmcnt(0)
	s_barrier
	v_lshlrev_b32_e32 v66, 2, v89
	v_or_b32_e32 v25, v25, v74
	v_or_b32_e32 v20, v20, v74
	v_add3_u32 v128, v9, v24, s25
	v_mov_b32_e32 v9, 0x3540
	v_add_u32_e32 v151, v67, v8
	v_add_u32_e32 v8, 0, v21
	s_mov_b32 s39, 0
	v_and_b32_e32 v102, 48, v39
	v_lshlrev_b32_e32 v26, 4, v26
	v_lshlrev_b32_e32 v42, 4, v42
	v_lshlrev_b32_e32 v25, 4, v25
	v_lshlrev_b32_e32 v20, 4, v20
	v_lshlrev_b32_e32 v74, 1, v65
	v_add_lshl_u32 v22, v37, v90, 1
	v_add_lshl_u32 v11, v11, v37, 1
	v_writelane_b32 v255, s97, 32
	v_lshl_or_b32 v129, v38, 4, v9
	s_add_i32 s3, 0, 0x15c00
	s_add_i32 s88, s22, 0
	s_add_i32 s89, s23, 0
	s_add_i32 s90, s24, 0
	v_add_u32_e32 v9, 0, v66
	v_add_u32_e32 v152, 0x12800, v8
	v_mbcnt_lo_u32_b32 v8, -1, 0
	s_mov_b64 s[52:53], s[38:39]
	v_add_u32_e32 v107, s70, v89
	v_lshlrev_b32_e32 v45, 4, v45
	v_cndmask_b32_e64 v65, 0, 1.0, vcc
	v_add_u32_e32 v127, 0x2d00, v103
	v_writelane_b32 v255, s29, 44
	v_or_b32_e32 v130, 0x3500, v102
	v_add_u32_e32 v131, v28, v68
	v_add_u32_e32 v132, v28, v26
	v_add_u32_e32 v133, v29, v42
	v_add_u32_e32 v134, v29, v69
	v_add_u32_e32 v135, s3, v70
	v_add_u32_e32 v136, s3, v71
	s_mov_b32 s86, 0x4038aa3b
	s_add_i32 s67, 0, 0x10000
	v_add_u32_e32 v137, v28, v72
	v_add_u32_e32 v138, v28, v25
	v_add_u32_e32 v139, v29, v75
	v_add_u32_e32 v140, v29, v20
	v_add_u32_e32 v141, s3, v73
	v_add_u32_e32 v142, s3, v74
	v_add_u32_e32 v143, v32, v33
	v_add_u32_e32 v145, v34, v35
	s_mov_b32 s87, 0xbfb8aa3b
	v_add_u32_e32 v146, v36, v44
	s_add_i32 s88, s88, 0x23900
	s_add_i32 s89, s89, 0x23900
	s_add_i32 s90, s90, 0x23900
	s_add_i32 s91, 0, 0x27900
	s_add_i32 s92, s81, 0x400
	s_add_i32 s93, s81, 0x800
	s_add_i32 s94, s81, 0xc00
	s_add_i32 s95, s81, 0x1400
	s_add_i32 s96, s81, 0x1800
	s_add_i32 s97, s81, 0x1c00
	s_add_i32 s3, 0, 0x16100
	s_add_i32 s69, 0, 0x18500
	v_mov_b32_e32 v147, 0xbf92477c
	v_add_u32_e32 v148, v40, v27
	s_xor_b64 s[54:55], s[26:27], -1
	v_add_u32_e32 v149, 0, v43
	v_add_u32_e32 v150, 0x12400, v9
	v_mov_b32_e32 v153, 0x3a27c5ac
	v_mbcnt_hi_u32_b32 v144, -1, v8
	v_add_u32_e32 v154, s71, v22
	v_add_u32_e32 v155, s71, v23
	v_add_u32_e32 v156, s71, v11
	s_mov_b32 s33, s28
	s_mov_b32 s29, 0
	v_add_u32_e32 v215, v92, v111
	v_add_u32_e32 v238, s69, v122
	v_add_u32_e32 v212, v91, v45
	v_add_u32_e32 v216, v94, v112
	v_add_u32_e32 v209, v95, v108
	v_add_u32_e32 v210, v96, v108
	v_add_u32_e32 v229, s3, v117
	v_add_u32_e32 v234, s67, v120
	v_add_u32_e32 v208, v94, v108
	v_add_u32_e32 v225, 0x15d80, v44
	v_add_u32_e32 v219, v93, v111
	v_add_u32_e32 v227, s67, v115
	v_xor_b32_e32 v243, 32, v144
	v_add_u32_e32 v233, s67, v119
	v_add_u32_e32 v207, v92, v45
	v_add_u32_e32 v237, s3, v122
	v_and_b32_e32 v241, 64, v144
	v_add_u32_e32 v224, s71, v114
	v_add_u32_e32 v235, s3, v121
	v_add_u32_e32 v21, 64, v241
	v_cmp_lt_i32_e32 vcc, v243, v21
	s_nop 1
	v_cndmask_b32_e32 v20, v144, v243, vcc
	v_lshlrev_b32_e32 v222, 2, v20
	v_add_u32_e32 v230, s69, v117
	v_add_u32_e32 v220, v91, v111
	v_add_u32_e32 v213, s67, v109
	v_or_b32_e32 v240, v102, v241
	v_xor_b32_e32 v242, 16, v144
	v_cmp_lt_i32_e32 vcc, v242, v21
	s_nop 1
	v_cndmask_b32_e32 v22, v144, v242, vcc
	v_lshlrev_b32_e32 v221, 2, v22
	v_add_u32_e32 v232, s69, v118
	v_add_u32_e32 v223, s67, v113
	v_add_u32_e32 v214, s71, v110
	v_add_u32_e32 v218, v96, v112
	v_add_u32_e32 v231, s3, v118
	v_add_u32_e32 v217, v95, v112
	v_add_u32_e32 v211, v93, v45
	v_add_u32_e32 v228, s67, v116
	v_add_u32_e32 v226, s83, v102
	v_add_u32_e32 v239, 0x12600, v97
	v_add_u32_e32 v236, s69, v121
	s_waitcnt vmcnt(0)
